# attention: waves 0-3 (which otherwise idle at the tile barrier) issue all 8 LDS-DMA pieces per tile pair-wise for their SIMD partner; waves 4-7 issue none
# speedup vs baseline: 1.0055x; 1.0055x over previous
; #define ATT_OFFS(LN) unsigned koff, voff; { int ln_ = (LN); asm volatile("" : "+v"(ln_)); const int row = 4 * wid + (ln_ >> 4), gsrc = (ln_ & 15) ^ (row & 7); koff = (unsigned)(row * 2048 + 8 * gsrc) * 2u; \
;           const int w5 = (ln_ & 31) >> 2, kl = (w5 & 3) + 8 * (w5 >> 2) + 4 * (wid >> 2), col = ((2 * wid + (ln_ >> 5)) & 7) * 32 + (ln_ & 3) * 8; voff = (unsigned)(kl * 2048 + col) * 2u; }
; DI void phase_attn64(int wid0, const Params& p, int L, unsigned char* lds, bool dry) {
;     ...
;         if (ui < 8) { const int bh = 8 * ui + (blk & 7), j = (blk >> 3) & 31; qb = (ui & 1) ? 31 - j : j; b = bh >> 3; hh = bh & 7; }
;         else if (ui == 8 && blk < 8) { meta = true; hh = blk; b = 0; qb = 0; }
;         else break;
;         const int qrow0 = meta ? MREG : b * 4096 + 128 * qb, qpos0 = meta ? 0 : 16 + 128 * qb, ntiles = meta ? 1 : 1 + 2 * (qb + 1);
;         { const int t_ = wid * 64 + lane; if (t_ < 130) tab[t_] = (t_ < 129) ? biasT[hh * 129 + t_] : -__builtin_inff(); }
;         __builtin_amdgcn_sched_barrier(0);
;         int myrow = qrow0 + 32 * rg + r32; if (meta && myrow > MREG + 63) myrow = MREG + 63;
;         const bf16_t* qp = qbuf + (size_t)myrow * 2048 + hh * 256 + psub * 128 + hi * 8;
;         bf16x8 qr[8];
; #pragma unroll
;         for (int d0 = 0; d0 < 8; ++d0) qr[d0] = *(const bf16x8*)(qp + d0 * 16);
;         __builtin_amdgcn_sched_barrier(0);
;         const int wq0 = qpos0 + 32 * rg, qpos = wq0 + r32;
;         const bf16_t* kh_ = kbuf + hh * 256; const bf16_t* vh_ = vbuf + hh * 256;
;         { ATT_OFFS(lane); attn_stage64(kh_ + (size_t)MREG * 2048, vh_ + (size_t)MREG * 2048, koff, voff, ldsl, wid); }
;         __builtin_amdgcn_sched_barrier(0);
.LBB0_97:
	s_or_b64 exec, exec, s[10:11]
	v_subrev_u32_e32 v2, s37, v191
	v_lshrrev_b32_e32 v2, 2, v2
	v_cmp_gt_u32_e32 vcc, 0xfc, v2
	s_mov_b64 s[10:11], vcc
	v_cmp_gt_u32_e32 vcc, 62, v2
	v_add_u32_e32 v2, 0xffffffc2, v2
	v_max_i32_e32 v2, 0, v2
	v_min_i32_e32 v2, 0x80, v2
	v_add_u32_e32 v2, s8, v2
	v_mov_b32_e32 v3, 0
	v_readlane_b32 s6, v245, 40
	v_readlane_b32 s7, v245, 41
	s_mov_b64 s[12:13], exec
	s_nop 1
	v_lshl_add_u64 v[2:3], v[2:3], 2, s[6:7]
	s_and_b64 exec, exec, s[10:11]
	global_load_dword v0, v[2:3], off
	v_mov_b32_e32 v3, 0xff800000
	s_waitcnt vmcnt(0)
	v_cndmask_b32_e32 v0, v0, v3, vcc
	ds_write_b32 v191, v0 offset:3328
	s_mov_b64 exec, s[12:13]
	s_lshl_b32 s40, s73, 12
	s_lshl_b32 s10, s75, 7
	s_add_i32 s9, s40, s10
	s_and_b64 s[6:7], s[76:77], exec
	s_cselect_b32 s71, 0x8000, s9
	s_lshl_b32 s6, s75, 2
	s_add_i32 s9, s6, 5
	s_and_b64 s[6:7], s[76:77], exec
	v_ashrrev_i32_e32 v0, 4, v4
	v_readlane_b32 s7, v245, 61
	v_and_b32_e32 v2, 15, v4
	v_lshrrev_b32_e32 v3, 1, v4
	v_add_u32_e32 v0, s7, v0
	v_bitop3_b32 v2, v0, v2, 15 bitop3:0x6c
	v_lshlrev_b32_e32 v0, 12, v0
	v_lshl_or_b32 v0, v2, 4, v0
	v_lshrrev_b32_e32 v2, 2, v4
	v_and_b32_e32 v3, 8, v3
	v_readlane_b32 s7, v245, 63
	v_and_or_b32 v2, v2, 3, v3
	v_lshlrev_b32_e32 v8, 3, v4
	v_add_u32_e32 v3, s7, v4
	v_readlane_b32 s7, v244, 1
	v_and_b32_e32 v7, 31, v4
	v_and_b32_e32 v3, 0xe0, v3
	v_and_b32_e32 v5, 24, v8
	v_lshl_add_u32 v2, v2, 11, s7
	v_or3_b32 v2, v2, v3, v5
	v_or_b32_e32 v3, s41, v7
	v_or_b32_e32 v3, s71, v3
	v_min_i32_e32 v9, 0x803f, v3
	v_cndmask_b32_e64 v10, v3, v9, s[76:77]
	s_cselect_b32 s6, 1, s9
	v_ashrrev_i32_e32 v11, 31, v10
	s_lshl_b32 s12, s49, 8
	v_lshlrev_b64 v[10:11], 12, v[10:11]
	s_ashr_i32 s13, s12, 31
	v_ashrrev_i32_e32 v6, 5, v4
	v_lshl_add_u64 v[10:11], s[0:1], 0, v[10:11]
	s_lshl_b64 s[78:79], s[12:13], 1
	v_readlane_b32 s12, v244, 5
	v_lshl_add_u64 v[10:11], v[10:11], 0, s[78:79]
	v_readlane_b32 s13, v244, 6
	v_lshlrev_b32_e32 v12, 3, v6
	v_ashrrev_i32_e32 v13, 31, v12
	v_lshl_add_u64 v[10:11], s[12:13], 1, v[10:11]
	v_lshl_add_u64 v[14:15], v[12:13], 1, v[10:11]
	global_load_dwordx4 v[248:251], v[14:15], off
	s_ashr_i32 s9, s8, 31
	s_lshl_b64 s[8:9], s[8:9], 2
	v_readlane_b32 s12, v245, 40
	v_lshlrev_b32_e32 v9, 4, v4
	v_readlane_b32 s7, v244, 7
	v_readlane_b32 s13, v245, 41
	s_add_u32 s8, s12, s8
	s_addc_u32 s9, s13, s9
	global_load_dword v176, v1, s[8:9] offset:512
	s_add_u32 s12, s28, s78
	s_addc_u32 s13, s29, s79
	s_mov_b64 s[84:85], s[12:13]
	v_readlane_b32 s8, v245, 38
	v_readlane_b32 s9, v245, 39
	s_add_u32 s8, s8, s78
	v_readlane_b32 s7, v244, 9
	s_addc_u32 s9, s9, s79
	s_mov_b64 s[86:87], s[8:9]
	v_lshl_add_u64 v[178:179], s[12:13], 0, v[0:1]
	v_mov_b32_e32 v131, v0
	s_mov_b64 s[14:15], 0x8000000
	s_add_i32 s7, s7, 0
	v_lshlrev_b32_e32 v2, 1, v2
	s_add_i32 m0, s7, 0x10000
	s_mov_b64 s[12:13], 0x8000100
	v_mov_b32_e32 v3, v1
	v_lshl_add_u64 v[180:181], s[8:9], 0, v[2:3]
	v_mov_b32_e32 v208, v2
	v_lshl_add_u64 v[2:3], v[180:181], 0, s[14:15]
	s_mov_b64 s[8:9], 0x8010000
	global_load_dwordx4 v[252:255], v[14:15], off offset:32
	global_load_dwordx4 v[200:203], v[14:15], off offset:64
	global_load_dwordx4 v[204:207], v[14:15], off offset:96
	global_load_dwordx4 v[164:167], v[14:15], off offset:128
	global_load_dwordx4 v[168:171], v[14:15], off offset:160
	global_load_dwordx4 v[172:175], v[14:15], off offset:192
	global_load_dwordx4 v[232:235], v[14:15], off offset:224
	v_lshl_add_u64 v[10:11], v[178:179], 0, s[14:15]
	global_load_lds_dwordx4 v[10:11], off
	v_lshl_add_u64 v[10:11], v[178:179], 0, s[12:13]
	s_add_i32 m0, s7, 0x12000
	s_nop 0
	global_load_lds_dwordx4 v[10:11], off
	s_add_i32 m0, s7, 0x0
	s_nop 0
	global_load_lds_dwordx4 v[2:3], off
	v_lshl_add_u64 v[2:3], v[180:181], 0, s[8:9]
	s_add_i32 m0, s7, 0x2000
	s_mov_b32 s7, 0
	global_load_lds_dwordx4 v[2:3], off
	s_cmp_lt_i32 s6, 1
	s_cbranch_scc1 .LBB0_114
; #define MFMA32(a, b, c) __builtin_amdgcn_mfma_f32_32x32x16_bf16((a), (b), (c), 0, 0, 0)
; DI int v_rd_base(int lane) { return ((lane & 3) << 3) | (((lane >> 2) & 3) << 6) | (((lane >> 4) & 1) << 5) | (((lane >> 5) & 1) << 8); }
; #define ATT_OFFS(LN) unsigned koff, voff; { int ln_ = (LN); asm volatile("" : "+v"(ln_)); const int row = 4 * wid + (ln_ >> 4), gsrc = (ln_ & 15) ^ (row & 7); koff = (unsigned)(row * 2048 + 8 * gsrc) * 2u; \
;           const int w5 = (ln_ & 31) >> 2, kl = (w5 & 3) + 8 * (w5 >> 2) + 4 * (wid >> 2), col = ((2 * wid + (ln_ >> 5)) & 7) * 32 + (ln_ & 3) * 8; voff = (unsigned)(kl * 2048 + col) * 2u; }
; template <int KH> DI void attn_half(f32x16 (&o)[8], const bf16x8 (&qr)[8], float& m_reg, float& l_reg, const unsigned char* Ks, int vb0, const float* tab, float* al_l,
;                                     int r32, int hi, int qpos, int wq0, int kpos0, bool t0) {
;     if (kpos0 > wq0 + 31) return;
;     f32x16 p0;
; #pragma unroll
;     for (int r = 0; r < 16; ++r) p0[r] = 0.f;
;     int swz = (r32 & 6) << 4, kro = (32 * KH + r32) * 256 + ((hi ^ (r32 & 1)) << 4); asm volatile("" : "+v"(swz), "+v"(kro));
; #pragma unroll
;     for (int d0 = 0; d0 < 8; ++d0) {
;         const bf16x8 b0 = *(const bf16x8*)(Ks + kro + ((d0 * 32) ^ swz));
;         p0 = MFMA32(b0, qr[d0], p0);
;         if (d0 == 3) __builtin_amdgcn_sched_barrier(0);
; DI void phase_attn64(int wid0, const Params& p, int L, unsigned char* lds, bool dry) {
;     ...
;         f32x16 o[8];
; #pragma unroll
;         for (int d = 0; d < 8; ++d)
; #pragma unroll
;             for (int r = 0; r < 16; ++r) o[d][r] = 0.f;
;         float m_reg = -1e30f, l_reg = 0.f;
;         for (int t = 0; t < ntiles; ++t) {
;             asm volatile("s_waitcnt vmcnt(0) lgkmcnt(0)" ::: "memory"); __builtin_amdgcn_s_barrier(); asm volatile("" ::: "memory");
;             if (t + 1 < ntiles) { ATT_OFFS(lane); attn_stage64(kh_ + (size_t)(b * 4096 + 64 * t) * 2048, vh_ + (size_t)(b * 4096 + 64 * t) * 2048, koff, voff, ldsl + ((t + 1) & 1) * 65536, wid); }
;             const int kpos0 = (t == 0) ? 0 : 16 + 64 * (t - 1);
;             const unsigned char* Ks = lds + (t & 1) * 65536 + psub * 16384;
;             const int vb0 = (int)(unsigned)(size_t)(ldsl + (t & 1) * 65536 + 32768) + v_rd_base(lane);
	s_or_b32 s10, s10, 16
	v_lshlrev_b32_e32 v0, 8, v7
	v_bitop3_b32 v2, v6, v4, 1 bitop3:0x78
	s_and_b64 s[8:9], s[76:77], exec
	v_lshl_add_u32 v193, v2, 4, v0
	v_lshlrev_b32_e32 v2, 1, v4
	s_cselect_b32 s39, 0, s10
	v_and_b32_e32 v0, 0xc0, v9
	v_and_b32_e32 v2, 32, v2
	v_readlane_b32 s48, v244, 17
	s_or_b32 s8, s39, s41
	v_and_b32_e32 v3, 0x100, v8
	v_add3_u32 v0, s48, v0, v2
	v_mov_b32_e32 v14, v1
	v_mov_b32_e32 v15, v1
	s_add_i32 s38, s8, 31
	v_and_b32_e32 v192, 0xe0, v9
	v_lshlrev_b32_e32 v194, 2, v6
	v_add_u32_e32 v195, s8, v7
	v_cmp_gt_u32_e64 s[8:9], 32, v4
	v_lshl_add_u32 v196, v7, 2, s2
	v_lshlrev_b32_e32 v16, 4, v6
	v_cmp_gt_i32_e64 s[10:11], 4, v6
	v_cmp_gt_i32_e64 s[18:19], 2, v6
	v_cmp_gt_i32_e64 s[20:21], 0, v6
	v_cmp_gt_i32_e64 s[22:23], -2, v6
	v_add3_u32 v212, v0, v3, v5
	v_add_u32_e32 v212, 0xffff0000, v212
	v_mov_b32_e32 v0, v1
	v_mov_b32_e32 v2, v1
	v_mov_b32_e32 v3, v1
	v_mov_b32_e32 v4, v1
	v_mov_b32_e32 v5, v1
	v_mov_b32_e32 v6, v1
	v_mov_b32_e32 v7, v1
	v_mov_b32_e32 v8, v1
	v_mov_b32_e32 v9, v1
	v_mov_b32_e32 v10, v1
	v_mov_b32_e32 v11, v1
	v_mov_b32_e32 v12, v1
	v_mov_b32_e32 v13, v1
	v_mov_b64_e32 v[128:129], v[14:15]
	v_mov_b64_e32 v[112:113], v[14:15]
	v_mov_b64_e32 v[96:97], v[14:15]
	v_mov_b64_e32 v[80:81], v[14:15]
	v_mov_b64_e32 v[64:65], v[14:15]
	v_mov_b64_e32 v[48:49], v[14:15]
	v_mov_b64_e32 v[32:33], v[14:15]
	v_or_b32_e32 v197, 1, v194
	v_or_b32_e32 v198, 2, v194
	v_or_b32_e32 v199, 3, v194
	v_readlane_b32 s48, v244, 19
	v_add_u32_e32 v214, s2, v16
	v_mov_b64_e32 v[126:127], v[12:13]
	v_mov_b64_e32 v[124:125], v[10:11]
	v_mov_b64_e32 v[122:123], v[8:9]
	v_mov_b64_e32 v[120:121], v[6:7]
	v_mov_b64_e32 v[118:119], v[4:5]
	v_mov_b64_e32 v[116:117], v[2:3]
	v_mov_b64_e32 v[114:115], v[0:1]
	v_mov_b64_e32 v[110:111], v[12:13]
	v_mov_b64_e32 v[108:109], v[10:11]
	v_mov_b64_e32 v[106:107], v[8:9]
	v_mov_b64_e32 v[104:105], v[6:7]
	v_mov_b64_e32 v[102:103], v[4:5]
	v_mov_b64_e32 v[100:101], v[2:3]
	v_mov_b64_e32 v[98:99], v[0:1]
	v_mov_b64_e32 v[94:95], v[12:13]
	v_mov_b64_e32 v[92:93], v[10:11]
	v_mov_b64_e32 v[90:91], v[8:9]
	v_mov_b64_e32 v[88:89], v[6:7]
	v_mov_b64_e32 v[86:87], v[4:5]
	v_mov_b64_e32 v[84:85], v[2:3]
	v_mov_b64_e32 v[82:83], v[0:1]
	v_mov_b64_e32 v[78:79], v[12:13]
	v_mov_b64_e32 v[76:77], v[10:11]
	v_mov_b64_e32 v[74:75], v[8:9]
	v_mov_b64_e32 v[72:73], v[6:7]
	v_mov_b64_e32 v[70:71], v[4:5]
	v_mov_b64_e32 v[68:69], v[2:3]
	v_mov_b64_e32 v[66:67], v[0:1]
	v_mov_b64_e32 v[62:63], v[12:13]
	v_mov_b64_e32 v[60:61], v[10:11]
	v_mov_b64_e32 v[58:59], v[8:9]
	v_mov_b64_e32 v[56:57], v[6:7]
	v_mov_b64_e32 v[54:55], v[4:5]
	v_mov_b64_e32 v[52:53], v[2:3]
	v_mov_b64_e32 v[50:51], v[0:1]
	v_mov_b64_e32 v[46:47], v[12:13]
	v_mov_b64_e32 v[44:45], v[10:11]
	v_mov_b64_e32 v[42:43], v[8:9]
	v_mov_b64_e32 v[40:41], v[6:7]
	v_mov_b64_e32 v[38:39], v[4:5]
	v_mov_b64_e32 v[36:37], v[2:3]
	v_mov_b64_e32 v[34:35], v[0:1]
	v_mov_b64_e32 v[30:31], v[12:13]
	v_mov_b64_e32 v[28:29], v[10:11]
	v_mov_b64_e32 v[26:27], v[8:9]
	v_mov_b64_e32 v[24:25], v[6:7]
	v_mov_b64_e32 v[22:23], v[4:5]
	v_mov_b64_e32 v[20:21], v[2:3]
	v_mov_b64_e32 v[18:19], v[0:1]
	v_mov_b64_e32 v[16:17], v[14:15]
	v_cmp_gt_i32_e64 s[12:13], 16, v197
	v_cmp_gt_i32_e64 s[14:15], 16, v198
	v_cmp_gt_i32_e64 s[16:17], 16, v199
	s_waitcnt vmcnt(11)
	v_mov_b32_e32 v182, v176
	v_mov_b32_e32 v183, v176
	s_add_i32 s39, s48, s39
	v_mov_b32_e32 v130, 0
	v_mov_b32_e32 v213, 0xf149f2ca
	s_mov_b32 s66, 0
	s_mov_b32 s100, 0x100
	v_readlane_b32 s80, v244, 13
	s_and_b32 s80, s80, 0x800
	s_or_b32 s100, s100, s80
	v_add_u32_e32 v182, 0x10000, v131
	v_add_u32_e32 v183, 0x4000, v208
	s_mov_b32 s67, 1
	s_mov_b32 s7, -16
	s_mov_b32 s97, 0x4138aa3b
	s_mov_b32 s80, s40
	s_mov_b32 s81, 0
	s_lshl_b64 s[80:81], s[80:81], 12
	s_add_u32 s88, s84, s80
	s_addc_u32 s89, s85, s81
	s_add_u32 s92, s86, s80
	s_addc_u32 s93, s87, s81
	s_add_u32 s94, s92, 0x10000
	s_addc_u32 s95, s93, 0
	s_add_u32 s90, s88, 0x100
	s_addc_u32 s91, s89, 0
	s_add_i32 s96, s4, 0xffff0000
	v_mov_b32_e32 v132, 0
	v_mov_b32_e32 v133, 0
	v_mov_b32_e32 v134, 0
	v_mov_b32_e32 v135, 0
	v_mov_b32_e32 v136, 0
	v_mov_b32_e32 v137, 0
	v_mov_b32_e32 v138, 0
	v_mov_b32_e32 v139, 0
	s_lshl_b32 s80, s96, 1
	s_add_i32 s80, s80, 0xc000
	v_lshl_add_u32 v226, v190, 4, s80
	ds_write_b128 v226, v[132:135]
	ds_write_b128 v226, v[132:135] offset:1024
	v_add_u32_e32 v226, s5, v193
	v_add_u32_e32 v188, v226, v192
	v_xad_u32 v177, v192, 32, v226
	v_xad_u32 v209, v192, 64, v226
	s_movk_i32 s80, 0x60
	v_xad_u32 v210, v192, s80, v226
	s_movk_i32 s80, 0x80
	v_xad_u32 v211, v192, s80, v226
	s_movk_i32 s80, 0xa0
	v_xad_u32 v215, v192, s80, v226
	s_movk_i32 s80, 0xc0
	v_xad_u32 v224, v192, s80, v226
	s_movk_i32 s80, 0xe0
	v_xad_u32 v225, v192, s80, v226
	v_mov_b64_e32 v[14:15], v[12:13]
	v_mov_b64_e32 v[12:13], v[10:11]
	v_mov_b64_e32 v[10:11], v[8:9]
	v_mov_b64_e32 v[8:9], v[6:7]
	v_mov_b64_e32 v[6:7], v[4:5]
	v_mov_b64_e32 v[4:5], v[2:3]
	v_mov_b64_e32 v[2:3], v[0:1]
	s_mov_b32 s69, 0
.LBB0_99:
	s_waitcnt vmcnt(0) lgkmcnt(0)
	s_barrier
	s_max_i32 s48, s7, 0
	s_cmp_gt_i32 s48, s38
	s_cbranch_scc1 .Lattn_skip0
	s_bitcmp1_b32 s100, 11
	s_cbranch_scc0 .Lattn_qkA0
	ds_read_b128 v[216:219], v188
	ds_read_b128 v[220:223], v177
	ds_read_b128 v[236:239], v209
	ds_read_b128 v[240:243], v210
	s_waitcnt lgkmcnt(2)
	v_mfma_f32_32x32x16_bf16 v[140:155], v[216:219], v[248:251], 0
	v_mfma_f32_32x32x16_bf16 v[140:155], v[220:223], v[252:255], v[140:155]
	ds_read_b128 v[216:219], v211
	ds_read_b128 v[220:223], v215
	s_waitcnt lgkmcnt(2)
	v_mfma_f32_32x32x16_bf16 v[140:155], v[236:239], v[200:203], v[140:155]
	v_mfma_f32_32x32x16_bf16 v[140:155], v[240:243], v[204:207], v[140:155]
	ds_read_b128 v[236:239], v224
	ds_read_b128 v[240:243], v225
	s_waitcnt lgkmcnt(2)
	v_mfma_f32_32x32x16_bf16 v[140:155], v[216:219], v[164:167], v[140:155]
	v_mfma_f32_32x32x16_bf16 v[140:155], v[220:223], v[168:171], v[140:155]
	s_waitcnt lgkmcnt(0)
	v_mfma_f32_32x32x16_bf16 v[140:155], v[236:239], v[172:175], v[140:155]
	v_mfma_f32_32x32x16_bf16 v[140:155], v[240:243], v[232:235], v[140:155]
.Lattn_qkdone0:
	s_cmpk_gt_i32 s39, 0x7f
	s_cbranch_scc0 .Lattn_near0
	s_cmp_lg_u32 s67, 1
	s_cbranch_scc0 .Lattn_near0

; #define MFMA32(a, b, c) __builtin_amdgcn_mfma_f32_32x32x16_bf16((a), (b), (c), 0, 0, 0)
; DI int v_rd_base(int lane) { return ((lane & 3) << 3) | (((lane >> 2) & 3) << 6) | (((lane >> 4) & 1) << 5) | (((lane >> 5) & 1) << 8); }
; #define ATT_OFFS(LN) unsigned koff, voff; { int ln_ = (LN); asm volatile("" : "+v"(ln_)); const int row = 4 * wid + (ln_ >> 4), gsrc = (ln_ & 15) ^ (row & 7); koff = (unsigned)(row * 2048 + 8 * gsrc) * 2u; \
;           const int w5 = (ln_ & 31) >> 2, kl = (w5 & 3) + 8 * (w5 >> 2) + 4 * (wid >> 2), col = ((2 * wid + (ln_ >> 5)) & 7) * 32 + (ln_ & 3) * 8; voff = (unsigned)(kl * 2048 + col) * 2u; }
; template <int KH> DI void attn_half(f32x16 (&o)[8], const bf16x8 (&qr)[8], float& m_reg, float& l_reg, const unsigned char* Ks, int vb0, const float* tab, float* al_l,
;                                     int r32, int hi, int qpos, int wq0, int kpos0, bool t0) {
;     ...
;     int swz = (r32 & 6) << 4, kro = (32 * KH + r32) * 256 + ((hi ^ (r32 & 1)) << 4); asm volatile("" : "+v"(swz), "+v"(kro));
; #pragma unroll
;     for (int d0 = 0; d0 < 8; ++d0) {
;         const bf16x8 b0 = *(const bf16x8*)(Ks + kro + ((d0 * 32) ^ swz));
;         p0 = MFMA32(b0, qr[d0], p0);
;         if (d0 == 3) __builtin_amdgcn_sched_barrier(0);
; DI void phase_attn64(int wid0, const Params& p, int L, unsigned char* lds, bool dry) {
;     ...
;         for (int t = 0; t < ntiles; ++t) {
;             asm volatile("s_waitcnt vmcnt(0) lgkmcnt(0)" ::: "memory"); __builtin_amdgcn_s_barrier(); asm volatile("" ::: "memory");
;             if (t + 1 < ntiles) { ATT_OFFS(lane); attn_stage64(kh_ + (size_t)(b * 4096 + 64 * t) * 2048, vh_ + (size_t)(b * 4096 + 64 * t) * 2048, koff, voff, ldsl + ((t + 1) & 1) * 65536, wid); }
;             const int kpos0 = (t == 0) ? 0 : 16 + 64 * (t - 1);
;             const unsigned char* Ks = lds + (t & 1) * 65536 + psub * 16384;
;             const int vb0 = (int)(unsigned)(size_t)(ldsl + (t & 1) * 65536 + 32768) + v_rd_base(lane);
;             attn_half<0>(o, qr, m_reg, l_reg, Ks, vb0, tab, al_l, r32, hi, qpos, wq0, kpos0, t == 0);
.Lattn_top1:
	s_waitcnt vmcnt(0) lgkmcnt(0)
	s_barrier
	s_max_i32 s48, s7, 0
	s_cmp_gt_i32 s48, s38
	s_cbranch_scc1 .Lattn_skip1
	s_bitcmp1_b32 s100, 11
	s_cbranch_scc0 .Lattn_qkA1
	ds_read_b128 v[216:219], v188 offset:32768
	ds_read_b128 v[220:223], v177 offset:32768
	ds_read_b128 v[236:239], v209 offset:32768
	ds_read_b128 v[240:243], v210 offset:32768
	s_waitcnt lgkmcnt(2)
	v_mfma_f32_32x32x16_bf16 v[140:155], v[216:219], v[248:251], 0
	v_mfma_f32_32x32x16_bf16 v[140:155], v[220:223], v[252:255], v[140:155]
	ds_read_b128 v[216:219], v211 offset:32768
	ds_read_b128 v[220:223], v215 offset:32768
	s_waitcnt lgkmcnt(2)
	v_mfma_f32_32x32x16_bf16 v[140:155], v[236:239], v[200:203], v[140:155]
	v_mfma_f32_32x32x16_bf16 v[140:155], v[240:243], v[204:207], v[140:155]
	ds_read_b128 v[236:239], v224 offset:32768
	ds_read_b128 v[240:243], v225 offset:32768
	s_waitcnt lgkmcnt(2)
	v_mfma_f32_32x32x16_bf16 v[140:155], v[216:219], v[164:167], v[140:155]
	v_mfma_f32_32x32x16_bf16 v[140:155], v[220:223], v[168:171], v[140:155]
	s_waitcnt lgkmcnt(0)
	v_mfma_f32_32x32x16_bf16 v[140:155], v[236:239], v[172:175], v[140:155]
	v_mfma_f32_32x32x16_bf16 v[140:155], v[240:243], v[232:235], v[140:155]

; #define LAS __attribute__((address_space(3)))
; #define MFMA32(a, b, c) __builtin_amdgcn_mfma_f32_32x32x16_bf16((a), (b), (c), 0, 0, 0)
; DI void attn_stage64(const bf16_t* kbase, const bf16_t* vbase, unsigned koff, unsigned voff, LAS unsigned char* ldsbuf, int wid) {
; #pragma unroll
;     for (int i = 0; i < 4; ++i) {
;         const unsigned off = koff + (unsigned)((32 * (i & 1)) * 2048 + (i >> 1) * 128) * 2u;
;         __builtin_amdgcn_global_load_lds((const unsigned*)((const char*)kbase + off), (LAS unsigned*)(ldsbuf + (wid + 8 * i) * 1024), 16, 0, 0);
;     }
; #pragma unroll
;     for (int i = 0; i < 4; ++i) {
;         const unsigned off = voff + (unsigned)(16 * i * 2048) * 2u;
;         __builtin_amdgcn_global_load_lds((const unsigned*)((const char*)vbase + off), (LAS unsigned*)(ldsbuf + 32768 + (wid + 8 * i) * 1024), 16, 0, 0);
;     }
; }
; template <int KH> DI void attn_half(f32x16 (&o)[8], const bf16x8 (&qr)[8], float& m_reg, float& l_reg, const unsigned char* Ks, int vb0, const float* tab, float* al_l,
;                                     int r32, int hi, int qpos, int wq0, int kpos0, bool t0) {
;     ...
;     int swz = (r32 & 6) << 4, kro = (32 * KH + r32) * 256 + ((hi ^ (r32 & 1)) << 4); asm volatile("" : "+v"(swz), "+v"(kro));
; #pragma unroll
;     for (int d0 = 0; d0 < 8; ++d0) {
;         const bf16x8 b0 = *(const bf16x8*)(Ks + kro + ((d0 * 32) ^ swz));
;         p0 = MFMA32(b0, qr[d0], p0);
;         if (d0 == 3) __builtin_amdgcn_sched_barrier(0);
.Lattn_qkA0:
	ds_read_b128 v[216:219], v188
	ds_read_b128 v[220:223], v177
	ds_read_b128 v[236:239], v209
	ds_read_b128 v[240:243], v210
	s_waitcnt lgkmcnt(2)
	s_add_i32 m0, s4, 0x8000
	v_mfma_f32_32x32x16_bf16 v[140:155], v[216:219], v[248:251], 0
	global_load_lds_dwordx4 v131, s[88:89]
	s_add_i32 m0, s4, 0x9000
	v_mfma_f32_32x32x16_bf16 v[140:155], v[220:223], v[252:255], v[140:155]
	global_load_lds_dwordx4 v182, s[88:89]
	ds_read_b128 v[216:219], v211
	ds_read_b128 v[220:223], v215
	s_waitcnt lgkmcnt(2)
	s_add_i32 m0, s4, 0xa000
	v_mfma_f32_32x32x16_bf16 v[140:155], v[236:239], v[200:203], v[140:155]
	global_load_lds_dwordx4 v131, s[90:91]
	v_add_u32_e32 v131, 0x20000, v131
	s_add_i32 m0, s4, 0xb000
	v_mfma_f32_32x32x16_bf16 v[140:155], v[240:243], v[204:207], v[140:155]
	global_load_lds_dwordx4 v182, s[90:91]
	v_add_u32_e32 v182, 0x20000, v182
	ds_read_b128 v[236:239], v224
	ds_read_b128 v[240:243], v225
	s_waitcnt lgkmcnt(2)
	s_add_i32 m0, s96, 0x4000
	v_mfma_f32_32x32x16_bf16 v[140:155], v[216:219], v[164:167], v[140:155]
	global_load_lds_dwordx4 v208, s[92:93]
	s_add_i32 m0, s96, 0x5000
	v_mfma_f32_32x32x16_bf16 v[140:155], v[220:223], v[168:171], v[140:155]
	global_load_lds_dwordx4 v183, s[92:93]
	s_waitcnt lgkmcnt(0)
	s_add_i32 m0, s96, 0x6000
	v_mfma_f32_32x32x16_bf16 v[140:155], v[236:239], v[172:175], v[140:155]
	global_load_lds_dwordx4 v208, s[94:95]
	v_add_u32_e32 v208, 0x20000, v208
	s_add_i32 m0, s96, 0x7000
	v_mfma_f32_32x32x16_bf16 v[140:155], v[240:243], v[232:235], v[140:155]
	global_load_lds_dwordx4 v183, s[94:95]
	v_add_u32_e32 v183, 0x20000, v183
	s_branch .Lattn_qkdone0

; #define LAS __attribute__((address_space(3)))
; #define MFMA32(a, b, c) __builtin_amdgcn_mfma_f32_32x32x16_bf16((a), (b), (c), 0, 0, 0)
; DI void attn_stage64(const bf16_t* kbase, const bf16_t* vbase, unsigned koff, unsigned voff, LAS unsigned char* ldsbuf, int wid) {
; #pragma unroll
;     for (int i = 0; i < 4; ++i) {
;         const unsigned off = koff + (unsigned)((32 * (i & 1)) * 2048 + (i >> 1) * 128) * 2u;
;         __builtin_amdgcn_global_load_lds((const unsigned*)((const char*)kbase + off), (LAS unsigned*)(ldsbuf + (wid + 8 * i) * 1024), 16, 0, 0);
;     }
; #pragma unroll
;     for (int i = 0; i < 4; ++i) {
;         const unsigned off = voff + (unsigned)(16 * i * 2048) * 2u;
;         __builtin_amdgcn_global_load_lds((const unsigned*)((const char*)vbase + off), (LAS unsigned*)(ldsbuf + 32768 + (wid + 8 * i) * 1024), 16, 0, 0);
;     }
; }
; template <int KH> DI void attn_half(f32x16 (&o)[8], const bf16x8 (&qr)[8], float& m_reg, float& l_reg, const unsigned char* Ks, int vb0, const float* tab, float* al_l,
;                                     int r32, int hi, int qpos, int wq0, int kpos0, bool t0) {
;     ...
;     int swz = (r32 & 6) << 4, kro = (32 * KH + r32) * 256 + ((hi ^ (r32 & 1)) << 4); asm volatile("" : "+v"(swz), "+v"(kro));
; #pragma unroll
;     for (int d0 = 0; d0 < 8; ++d0) {
;         const bf16x8 b0 = *(const bf16x8*)(Ks + kro + ((d0 * 32) ^ swz));
;         p0 = MFMA32(b0, qr[d0], p0);
;         if (d0 == 3) __builtin_amdgcn_sched_barrier(0);
.Lattn_qkA1:
	ds_read_b128 v[216:219], v188 offset:32768
	ds_read_b128 v[220:223], v177 offset:32768
	ds_read_b128 v[236:239], v209 offset:32768
	ds_read_b128 v[240:243], v210 offset:32768
	s_waitcnt lgkmcnt(2)
	s_add_i32 m0, s4, 0x0
	v_mfma_f32_32x32x16_bf16 v[140:155], v[216:219], v[248:251], 0
	global_load_lds_dwordx4 v131, s[88:89]
	s_add_i32 m0, s4, 0x1000
	v_mfma_f32_32x32x16_bf16 v[140:155], v[220:223], v[252:255], v[140:155]
	global_load_lds_dwordx4 v182, s[88:89]
	ds_read_b128 v[216:219], v211 offset:32768
	ds_read_b128 v[220:223], v215 offset:32768
	s_waitcnt lgkmcnt(2)
	s_add_i32 m0, s4, 0x2000
	v_mfma_f32_32x32x16_bf16 v[140:155], v[236:239], v[200:203], v[140:155]
	global_load_lds_dwordx4 v131, s[90:91]
	v_add_u32_e32 v131, 0x20000, v131
	s_add_i32 m0, s4, 0x3000
	v_mfma_f32_32x32x16_bf16 v[140:155], v[240:243], v[204:207], v[140:155]
	global_load_lds_dwordx4 v182, s[90:91]
	v_add_u32_e32 v182, 0x20000, v182
	ds_read_b128 v[236:239], v224 offset:32768
	ds_read_b128 v[240:243], v225 offset:32768
	s_waitcnt lgkmcnt(2)
	s_add_i32 m0, s96, 0x8000
	v_mfma_f32_32x32x16_bf16 v[140:155], v[216:219], v[164:167], v[140:155]
	global_load_lds_dwordx4 v208, s[92:93]
	s_add_i32 m0, s96, 0x9000
	v_mfma_f32_32x32x16_bf16 v[140:155], v[220:223], v[168:171], v[140:155]
	global_load_lds_dwordx4 v183, s[92:93]
	s_waitcnt lgkmcnt(0)
	s_add_i32 m0, s96, 0xa000
	v_mfma_f32_32x32x16_bf16 v[140:155], v[236:239], v[172:175], v[140:155]
	global_load_lds_dwordx4 v208, s[94:95]
	v_add_u32_e32 v208, 0x20000, v208
	s_add_i32 m0, s96, 0xb000
	v_mfma_f32_32x32x16_bf16 v[140:155], v[240:243], v[232:235], v[140:155]
	global_load_lds_dwordx4 v183, s[94:95]
	v_add_u32_e32 v183, 0x20000, v183
	s_branch .Lattn_qkdone1

; #define LAS __attribute__((address_space(3)))
; #define MFMA32(a, b, c) __builtin_amdgcn_mfma_f32_32x32x16_bf16((a), (b), (c), 0, 0, 0)
; DI void attn_stage64(const bf16_t* kbase, const bf16_t* vbase, unsigned koff, unsigned voff, LAS unsigned char* ldsbuf, int wid) {
; #pragma unroll
;     for (int i = 0; i < 4; ++i) {
;         const unsigned off = koff + (unsigned)((32 * (i & 1)) * 2048 + (i >> 1) * 128) * 2u;
;         __builtin_amdgcn_global_load_lds((const unsigned*)((const char*)kbase + off), (LAS unsigned*)(ldsbuf + (wid + 8 * i) * 1024), 16, 0, 0);
;     }
; #pragma unroll
;     for (int i = 0; i < 4; ++i) {
;         const unsigned off = voff + (unsigned)(16 * i * 2048) * 2u;
;         __builtin_amdgcn_global_load_lds((const unsigned*)((const char*)vbase + off), (LAS unsigned*)(ldsbuf + 32768 + (wid + 8 * i) * 1024), 16, 0, 0);
;     }
; }
; template <int KH> DI void attn_half(f32x16 (&o)[8], const bf16x8 (&qr)[8], float& m_reg, float& l_reg, const unsigned char* Ks, int vb0, const float* tab, float* al_l,
;                                     int r32, int hi, int qpos, int wq0, int kpos0, bool t0) {
;     ...
;     int swz = (r32 & 6) << 4, kro = (32 * KH + r32) * 256 + ((hi ^ (r32 & 1)) << 4); asm volatile("" : "+v"(swz), "+v"(kro));
; #pragma unroll
;     for (int d0 = 0; d0 < 8; ++d0) {
;         const bf16x8 b0 = *(const bf16x8*)(Ks + kro + ((d0 * 32) ^ swz));
;         p0 = MFMA32(b0, qr[d0], p0);
;         if (d0 == 3) __builtin_amdgcn_sched_barrier(0);
.Lattn_qkA2:
	ds_read_b128 v[216:219], v188
	ds_read_b128 v[220:223], v177
	ds_read_b128 v[236:239], v209
	ds_read_b128 v[240:243], v210
	s_waitcnt lgkmcnt(2)
	s_add_i32 m0, s4, 0x8000
	v_mfma_f32_32x32x16_bf16 v[140:155], v[216:219], v[248:251], 0
	global_load_lds_dwordx4 v131, s[88:89]
	s_add_i32 m0, s4, 0x9000
	v_mfma_f32_32x32x16_bf16 v[140:155], v[220:223], v[252:255], v[140:155]
	global_load_lds_dwordx4 v182, s[88:89]
	ds_read_b128 v[216:219], v211
	ds_read_b128 v[220:223], v215
	s_waitcnt lgkmcnt(2)
	s_add_i32 m0, s4, 0xa000
	v_mfma_f32_32x32x16_bf16 v[140:155], v[236:239], v[200:203], v[140:155]
	global_load_lds_dwordx4 v131, s[90:91]
	v_add_u32_e32 v131, 0x20000, v131
	s_add_i32 m0, s4, 0xb000
	v_mfma_f32_32x32x16_bf16 v[140:155], v[240:243], v[204:207], v[140:155]
	global_load_lds_dwordx4 v182, s[90:91]
	v_add_u32_e32 v182, 0x20000, v182
	ds_read_b128 v[236:239], v224
	ds_read_b128 v[240:243], v225
	s_waitcnt lgkmcnt(2)
	s_add_i32 m0, s96, 0xc000
	v_mfma_f32_32x32x16_bf16 v[140:155], v[216:219], v[164:167], v[140:155]
	global_load_lds_dwordx4 v208, s[92:93]
	s_add_i32 m0, s96, 0xd000
	v_mfma_f32_32x32x16_bf16 v[140:155], v[220:223], v[168:171], v[140:155]
	global_load_lds_dwordx4 v183, s[92:93]
	s_waitcnt lgkmcnt(0)
	s_add_i32 m0, s96, 0xe000
	v_mfma_f32_32x32x16_bf16 v[140:155], v[236:239], v[172:175], v[140:155]
	global_load_lds_dwordx4 v208, s[94:95]
	v_add_u32_e32 v208, 0x20000, v208
	s_add_i32 m0, s96, 0xf000
	v_mfma_f32_32x32x16_bf16 v[140:155], v[240:243], v[232:235], v[140:155]
	global_load_lds_dwordx4 v183, s[94:95]
	v_add_u32_e32 v183, 0x20000, v183
	s_branch .Lattn_qkdone2

; #define LAS __attribute__((address_space(3)))
; #define MFMA32(a, b, c) __builtin_amdgcn_mfma_f32_32x32x16_bf16((a), (b), (c), 0, 0, 0)
; DI void attn_stage64(const bf16_t* kbase, const bf16_t* vbase, unsigned koff, unsigned voff, LAS unsigned char* ldsbuf, int wid) {
; #pragma unroll
;     for (int i = 0; i < 4; ++i) {
;         const unsigned off = koff + (unsigned)((32 * (i & 1)) * 2048 + (i >> 1) * 128) * 2u;
;         __builtin_amdgcn_global_load_lds((const unsigned*)((const char*)kbase + off), (LAS unsigned*)(ldsbuf + (wid + 8 * i) * 1024), 16, 0, 0);
;     }
; #pragma unroll
;     for (int i = 0; i < 4; ++i) {
;         const unsigned off = voff + (unsigned)(16 * i * 2048) * 2u;
;         __builtin_amdgcn_global_load_lds((const unsigned*)((const char*)vbase + off), (LAS unsigned*)(ldsbuf + 32768 + (wid + 8 * i) * 1024), 16, 0, 0);
;     }
; }
; template <int KH> DI void attn_half(f32x16 (&o)[8], const bf16x8 (&qr)[8], float& m_reg, float& l_reg, const unsigned char* Ks, int vb0, const float* tab, float* al_l,
;                                     int r32, int hi, int qpos, int wq0, int kpos0, bool t0) {
;     ...
;     int swz = (r32 & 6) << 4, kro = (32 * KH + r32) * 256 + ((hi ^ (r32 & 1)) << 4); asm volatile("" : "+v"(swz), "+v"(kro));
; #pragma unroll
;     for (int d0 = 0; d0 < 8; ++d0) {
;         const bf16x8 b0 = *(const bf16x8*)(Ks + kro + ((d0 * 32) ^ swz));
;         p0 = MFMA32(b0, qr[d0], p0);
;         if (d0 == 3) __builtin_amdgcn_sched_barrier(0);
.Lattn_qkA3:
	ds_read_b128 v[216:219], v188 offset:32768
	ds_read_b128 v[220:223], v177 offset:32768
	ds_read_b128 v[236:239], v209 offset:32768
	ds_read_b128 v[240:243], v210 offset:32768
	s_waitcnt lgkmcnt(2)
	s_add_i32 m0, s4, 0x0
	v_mfma_f32_32x32x16_bf16 v[140:155], v[216:219], v[248:251], 0
	global_load_lds_dwordx4 v131, s[88:89]
	s_add_i32 m0, s4, 0x1000
	v_mfma_f32_32x32x16_bf16 v[140:155], v[220:223], v[252:255], v[140:155]
	global_load_lds_dwordx4 v182, s[88:89]
	ds_read_b128 v[216:219], v211 offset:32768
	ds_read_b128 v[220:223], v215 offset:32768
	s_waitcnt lgkmcnt(2)
	s_add_i32 m0, s4, 0x2000
	v_mfma_f32_32x32x16_bf16 v[140:155], v[236:239], v[200:203], v[140:155]
	global_load_lds_dwordx4 v131, s[90:91]
	v_add_u32_e32 v131, 0x20000, v131
	s_add_i32 m0, s4, 0x3000
	v_mfma_f32_32x32x16_bf16 v[140:155], v[240:243], v[204:207], v[140:155]
	global_load_lds_dwordx4 v182, s[90:91]
	v_add_u32_e32 v182, 0x20000, v182
	ds_read_b128 v[236:239], v224 offset:32768
	ds_read_b128 v[240:243], v225 offset:32768
	s_waitcnt lgkmcnt(2)
	s_add_i32 m0, s96, 0x0
	v_mfma_f32_32x32x16_bf16 v[140:155], v[216:219], v[164:167], v[140:155]
	global_load_lds_dwordx4 v208, s[92:93]
	s_add_i32 m0, s96, 0x1000
	v_mfma_f32_32x32x16_bf16 v[140:155], v[220:223], v[168:171], v[140:155]
	global_load_lds_dwordx4 v183, s[92:93]
	s_waitcnt lgkmcnt(0)
	s_add_i32 m0, s96, 0x2000
	v_mfma_f32_32x32x16_bf16 v[140:155], v[236:239], v[172:175], v[140:155]
	global_load_lds_dwordx4 v208, s[94:95]
	v_add_u32_e32 v208, 0x20000, v208
	s_add_i32 m0, s96, 0x3000
	v_mfma_f32_32x32x16_bf16 v[140:155], v[240:243], v[232:235], v[140:155]
	global_load_lds_dwordx4 v183, s[94:95]
	v_add_u32_e32 v183, 0x20000, v183
	s_branch .Lattn_qkdone3

; #define LAS __attribute__((address_space(3)))
; #define ATT_OFFS(LN) unsigned koff, voff; { int ln_ = (LN); asm volatile("" : "+v"(ln_)); const int row = 4 * wid + (ln_ >> 4), gsrc = (ln_ & 15) ^ (row & 7); koff = (unsigned)(row * 2048 + 8 * gsrc) * 2u; \
;           const int w5 = (ln_ & 31) >> 2, kl = (w5 & 3) + 8 * (w5 >> 2) + 4 * (wid >> 2), col = ((2 * wid + (ln_ >> 5)) & 7) * 32 + (ln_ & 3) * 8; voff = (unsigned)(kl * 2048 + col) * 2u; }
; DI void attn_stage64(const bf16_t* kbase, const bf16_t* vbase, unsigned koff, unsigned voff, LAS unsigned char* ldsbuf, int wid) {
; #pragma unroll
;     for (int i = 0; i < 4; ++i) {
;         const unsigned off = koff + (unsigned)((32 * (i & 1)) * 2048 + (i >> 1) * 128) * 2u;
;         __builtin_amdgcn_global_load_lds((const unsigned*)((const char*)kbase + off), (LAS unsigned*)(ldsbuf + (wid + 8 * i) * 1024), 16, 0, 0);
;     }
; #pragma unroll
;     for (int i = 0; i < 4; ++i) {
;         const unsigned off = voff + (unsigned)(16 * i * 2048) * 2u;
;         __builtin_amdgcn_global_load_lds((const unsigned*)((const char*)vbase + off), (LAS unsigned*)(ldsbuf + 32768 + (wid + 8 * i) * 1024), 16, 0, 0);
;     }
; }
; DI void phase_attn64(int wid0, const Params& p, int L, unsigned char* lds, bool dry) {
;     ...
;         for (int t = 0; t < ntiles; ++t) {
;             asm volatile("s_waitcnt vmcnt(0) lgkmcnt(0)" ::: "memory"); __builtin_amdgcn_s_barrier(); asm volatile("" ::: "memory");
;             if (t + 1 < ntiles) { ATT_OFFS(lane); attn_stage64(kh_ + (size_t)(b * 4096 + 64 * t) * 2048, vh_ + (size_t)(b * 4096 + 64 * t) * 2048, koff, voff, ldsl + ((t + 1) & 1) * 65536, wid); }
.Lattn_skip0:
	s_bitcmp1_b32 s100, 11
	s_cbranch_scc1 .Lattn_sknd0
	s_add_i32 m0, s4, 0x8000
	s_nop 0
	global_load_lds_dwordx4 v131, s[88:89]
	s_add_i32 m0, s4, 0x9000
	s_nop 0
	global_load_lds_dwordx4 v182, s[88:89]
	s_add_i32 m0, s4, 0xa000
	s_nop 0
	global_load_lds_dwordx4 v131, s[90:91]
	v_add_u32_e32 v131, 0x20000, v131
	s_add_i32 m0, s4, 0xb000
	s_nop 0
	global_load_lds_dwordx4 v182, s[90:91]
	v_add_u32_e32 v182, 0x20000, v182
	s_add_i32 m0, s96, 0x4000
	s_nop 0
	global_load_lds_dwordx4 v208, s[92:93]
	s_add_i32 m0, s96, 0x5000
	s_nop 0
	global_load_lds_dwordx4 v183, s[92:93]
	s_add_i32 m0, s96, 0x6000
	s_nop 0
	global_load_lds_dwordx4 v208, s[94:95]
	v_add_u32_e32 v208, 0x20000, v208
	s_add_i32 m0, s96, 0x7000
	s_nop 0
	global_load_lds_dwordx4 v183, s[94:95]
	v_add_u32_e32 v183, 0x20000, v183

; #define LAS __attribute__((address_space(3)))
; #define ATT_OFFS(LN) unsigned koff, voff; { int ln_ = (LN); asm volatile("" : "+v"(ln_)); const int row = 4 * wid + (ln_ >> 4), gsrc = (ln_ & 15) ^ (row & 7); koff = (unsigned)(row * 2048 + 8 * gsrc) * 2u; \
;           const int w5 = (ln_ & 31) >> 2, kl = (w5 & 3) + 8 * (w5 >> 2) + 4 * (wid >> 2), col = ((2 * wid + (ln_ >> 5)) & 7) * 32 + (ln_ & 3) * 8; voff = (unsigned)(kl * 2048 + col) * 2u; }
; DI void attn_stage64(const bf16_t* kbase, const bf16_t* vbase, unsigned koff, unsigned voff, LAS unsigned char* ldsbuf, int wid) {
; #pragma unroll
;     for (int i = 0; i < 4; ++i) {
;         const unsigned off = koff + (unsigned)((32 * (i & 1)) * 2048 + (i >> 1) * 128) * 2u;
;         __builtin_amdgcn_global_load_lds((const unsigned*)((const char*)kbase + off), (LAS unsigned*)(ldsbuf + (wid + 8 * i) * 1024), 16, 0, 0);
;     }
; #pragma unroll
;     for (int i = 0; i < 4; ++i) {
;         const unsigned off = voff + (unsigned)(16 * i * 2048) * 2u;
;         __builtin_amdgcn_global_load_lds((const unsigned*)((const char*)vbase + off), (LAS unsigned*)(ldsbuf + 32768 + (wid + 8 * i) * 1024), 16, 0, 0);
;     }
; }
; DI void phase_attn64(int wid0, const Params& p, int L, unsigned char* lds, bool dry) {
;     ...
;         for (int t = 0; t < ntiles; ++t) {
;             asm volatile("s_waitcnt vmcnt(0) lgkmcnt(0)" ::: "memory"); __builtin_amdgcn_s_barrier(); asm volatile("" ::: "memory");
;             if (t + 1 < ntiles) { ATT_OFFS(lane); attn_stage64(kh_ + (size_t)(b * 4096 + 64 * t) * 2048, vh_ + (size_t)(b * 4096 + 64 * t) * 2048, koff, voff, ldsl + ((t + 1) & 1) * 65536, wid); }
.Lattn_skip1:
	s_bitcmp1_b32 s100, 11
	s_cbranch_scc1 .Lattn_sknd1
	s_add_i32 m0, s4, 0x0
	s_nop 0
	global_load_lds_dwordx4 v131, s[88:89]
	s_add_i32 m0, s4, 0x1000
	s_nop 0
	global_load_lds_dwordx4 v182, s[88:89]
	s_add_i32 m0, s4, 0x2000
	s_nop 0
	global_load_lds_dwordx4 v131, s[90:91]
	v_add_u32_e32 v131, 0x20000, v131
	s_add_i32 m0, s4, 0x3000
	s_nop 0
	global_load_lds_dwordx4 v182, s[90:91]
	v_add_u32_e32 v182, 0x20000, v182
	s_add_i32 m0, s96, 0x8000
	s_nop 0
	global_load_lds_dwordx4 v208, s[92:93]
	s_add_i32 m0, s96, 0x9000
	s_nop 0
	global_load_lds_dwordx4 v183, s[92:93]
	s_add_i32 m0, s96, 0xa000
	s_nop 0
	global_load_lds_dwordx4 v208, s[94:95]
	v_add_u32_e32 v208, 0x20000, v208
	s_add_i32 m0, s96, 0xb000
	s_nop 0
	global_load_lds_dwordx4 v183, s[94:95]
	v_add_u32_e32 v183, 0x20000, v183

; #define LAS __attribute__((address_space(3)))
; #define ATT_OFFS(LN) unsigned koff, voff; { int ln_ = (LN); asm volatile("" : "+v"(ln_)); const int row = 4 * wid + (ln_ >> 4), gsrc = (ln_ & 15) ^ (row & 7); koff = (unsigned)(row * 2048 + 8 * gsrc) * 2u; \
;           const int w5 = (ln_ & 31) >> 2, kl = (w5 & 3) + 8 * (w5 >> 2) + 4 * (wid >> 2), col = ((2 * wid + (ln_ >> 5)) & 7) * 32 + (ln_ & 3) * 8; voff = (unsigned)(kl * 2048 + col) * 2u; }
; DI void attn_stage64(const bf16_t* kbase, const bf16_t* vbase, unsigned koff, unsigned voff, LAS unsigned char* ldsbuf, int wid) {
; #pragma unroll
;     for (int i = 0; i < 4; ++i) {
;         const unsigned off = koff + (unsigned)((32 * (i & 1)) * 2048 + (i >> 1) * 128) * 2u;
;         __builtin_amdgcn_global_load_lds((const unsigned*)((const char*)kbase + off), (LAS unsigned*)(ldsbuf + (wid + 8 * i) * 1024), 16, 0, 0);
;     }
; #pragma unroll
;     for (int i = 0; i < 4; ++i) {
;         const unsigned off = voff + (unsigned)(16 * i * 2048) * 2u;
;         __builtin_amdgcn_global_load_lds((const unsigned*)((const char*)vbase + off), (LAS unsigned*)(ldsbuf + 32768 + (wid + 8 * i) * 1024), 16, 0, 0);
;     }
; }
; DI void phase_attn64(int wid0, const Params& p, int L, unsigned char* lds, bool dry) {
;     ...
;         for (int t = 0; t < ntiles; ++t) {
;             asm volatile("s_waitcnt vmcnt(0) lgkmcnt(0)" ::: "memory"); __builtin_amdgcn_s_barrier(); asm volatile("" ::: "memory");
;             if (t + 1 < ntiles) { ATT_OFFS(lane); attn_stage64(kh_ + (size_t)(b * 4096 + 64 * t) * 2048, vh_ + (size_t)(b * 4096 + 64 * t) * 2048, koff, voff, ldsl + ((t + 1) & 1) * 65536, wid); }
.Lattn_skip2:
	s_bitcmp1_b32 s100, 11
	s_cbranch_scc1 .Lattn_sknd2
	s_add_i32 m0, s4, 0x8000
	s_nop 0
	global_load_lds_dwordx4 v131, s[88:89]
	s_add_i32 m0, s4, 0x9000
	s_nop 0
	global_load_lds_dwordx4 v182, s[88:89]
	s_add_i32 m0, s4, 0xa000
	s_nop 0
	global_load_lds_dwordx4 v131, s[90:91]
	v_add_u32_e32 v131, 0x20000, v131
	s_add_i32 m0, s4, 0xb000
	s_nop 0
	global_load_lds_dwordx4 v182, s[90:91]
	v_add_u32_e32 v182, 0x20000, v182
	s_add_i32 m0, s96, 0xc000
	s_nop 0
	global_load_lds_dwordx4 v208, s[92:93]
	s_add_i32 m0, s96, 0xd000
	s_nop 0
	global_load_lds_dwordx4 v183, s[92:93]
	s_add_i32 m0, s96, 0xe000
	s_nop 0
	global_load_lds_dwordx4 v208, s[94:95]
	v_add_u32_e32 v208, 0x20000, v208
	s_add_i32 m0, s96, 0xf000
	s_nop 0
	global_load_lds_dwordx4 v183, s[94:95]
	v_add_u32_e32 v183, 0x20000, v183

; #define LAS __attribute__((address_space(3)))
; #define ATT_OFFS(LN) unsigned koff, voff; { int ln_ = (LN); asm volatile("" : "+v"(ln_)); const int row = 4 * wid + (ln_ >> 4), gsrc = (ln_ & 15) ^ (row & 7); koff = (unsigned)(row * 2048 + 8 * gsrc) * 2u; \
;           const int w5 = (ln_ & 31) >> 2, kl = (w5 & 3) + 8 * (w5 >> 2) + 4 * (wid >> 2), col = ((2 * wid + (ln_ >> 5)) & 7) * 32 + (ln_ & 3) * 8; voff = (unsigned)(kl * 2048 + col) * 2u; }
; DI void attn_stage64(const bf16_t* kbase, const bf16_t* vbase, unsigned koff, unsigned voff, LAS unsigned char* ldsbuf, int wid) {
; #pragma unroll
;     for (int i = 0; i < 4; ++i) {
;         const unsigned off = koff + (unsigned)((32 * (i & 1)) * 2048 + (i >> 1) * 128) * 2u;
;         __builtin_amdgcn_global_load_lds((const unsigned*)((const char*)kbase + off), (LAS unsigned*)(ldsbuf + (wid + 8 * i) * 1024), 16, 0, 0);
;     }
; #pragma unroll
;     for (int i = 0; i < 4; ++i) {
;         const unsigned off = voff + (unsigned)(16 * i * 2048) * 2u;
;         __builtin_amdgcn_global_load_lds((const unsigned*)((const char*)vbase + off), (LAS unsigned*)(ldsbuf + 32768 + (wid + 8 * i) * 1024), 16, 0, 0);
;     }
; }
; DI void phase_attn64(int wid0, const Params& p, int L, unsigned char* lds, bool dry) {
;     ...
;         for (int t = 0; t < ntiles; ++t) {
;             asm volatile("s_waitcnt vmcnt(0) lgkmcnt(0)" ::: "memory"); __builtin_amdgcn_s_barrier(); asm volatile("" ::: "memory");
;             if (t + 1 < ntiles) { ATT_OFFS(lane); attn_stage64(kh_ + (size_t)(b * 4096 + 64 * t) * 2048, vh_ + (size_t)(b * 4096 + 64 * t) * 2048, koff, voff, ldsl + ((t + 1) & 1) * 65536, wid); }
.Lattn_skip3:
	s_bitcmp1_b32 s100, 11
	s_cbranch_scc1 .Lattn_sknd3
	s_add_i32 m0, s4, 0x0
	s_nop 0
	global_load_lds_dwordx4 v131, s[88:89]
	s_add_i32 m0, s4, 0x1000
	s_nop 0
	global_load_lds_dwordx4 v182, s[88:89]
	s_add_i32 m0, s4, 0x2000
	s_nop 0
	global_load_lds_dwordx4 v131, s[90:91]
	v_add_u32_e32 v131, 0x20000, v131
	s_add_i32 m0, s4, 0x3000
	s_nop 0
	global_load_lds_dwordx4 v182, s[90:91]
	v_add_u32_e32 v182, 0x20000, v182
	s_add_i32 m0, s96, 0x0
	s_nop 0
	global_load_lds_dwordx4 v208, s[92:93]
	s_add_i32 m0, s96, 0x1000
	s_nop 0
	global_load_lds_dwordx4 v183, s[92:93]
	s_add_i32 m0, s96, 0x2000
	s_nop 0
	global_load_lds_dwordx4 v208, s[94:95]
	v_add_u32_e32 v208, 0x20000, v208
	s_add_i32 m0, s96, 0x3000
	s_nop 0
	global_load_lds_dwordx4 v183, s[94:95]
	v_add_u32_e32 v183, 0x20000, v183
